# NSA window path: 57-instr canonicalising max tree replaced by 17-op v_max3 double chain
# baseline (speedup 1.0000x reference)
.LBB0_837:
	s_mov_b32 s4, 0xff800000
	v_max3_f32 v2, v3, v4, v5
	v_max3_f32 v48, v168, v169, v170
	v_max3_f32 v2, v2, v6, v7
	v_max3_f32 v48, v48, v171, v172
	v_max3_f32 v2, v2, v8, v10
	v_max3_f32 v48, v48, v174, v175
	v_max3_f32 v2, v2, v9, v11
	v_max3_f32 v48, v48, v176, v179
	v_max3_f32 v2, v2, v12, v13
	v_max3_f32 v48, v48, v173, v178
	v_max3_f32 v2, v2, v14, v15
	v_max3_f32 v48, v48, v177, v181
	v_max3_f32 v2, v2, v166, v167
	v_max3_f32 v48, v48, v180, v198
	v_max3_f32 v48, v48, v197, v199
	v_max_f32_e32 v2, v2, v48
	v_mov_b32_e32 v48, v2
	s_nop 1
	v_permlane32_swap_b32_e32 v2, v48
	v_max3_f32 v161, v160, v2, v48
	v_sub_f32_e32 v2, v160, v161
	v_exp_f32_e32 v2, v2
	v_cmp_neq_f32_e32 vcc, 1.0, v2
	s_cbranch_vccz .LBB0_839
	v_pk_mul_f32 v[46:47], v[46:47], v[2:3] op_sel_hi:[1,0]
	v_pk_mul_f32 v[44:45], v[44:45], v[2:3] op_sel_hi:[1,0]
	v_pk_mul_f32 v[42:43], v[42:43], v[2:3] op_sel_hi:[1,0]
	v_pk_mul_f32 v[40:41], v[40:41], v[2:3] op_sel_hi:[1,0]
	v_pk_mul_f32 v[38:39], v[38:39], v[2:3] op_sel_hi:[1,0]
	v_pk_mul_f32 v[36:37], v[36:37], v[2:3] op_sel_hi:[1,0]
	v_pk_mul_f32 v[34:35], v[34:35], v[2:3] op_sel_hi:[1,0]
	v_pk_mul_f32 v[32:33], v[32:33], v[2:3] op_sel_hi:[1,0]
	v_pk_mul_f32 v[30:31], v[30:31], v[2:3] op_sel_hi:[1,0]
	v_pk_mul_f32 v[28:29], v[28:29], v[2:3] op_sel_hi:[1,0]
	v_pk_mul_f32 v[26:27], v[26:27], v[2:3] op_sel_hi:[1,0]
	v_pk_mul_f32 v[24:25], v[24:25], v[2:3] op_sel_hi:[1,0]
	v_pk_mul_f32 v[22:23], v[22:23], v[2:3] op_sel_hi:[1,0]
	v_pk_mul_f32 v[20:21], v[20:21], v[2:3] op_sel_hi:[1,0]
	v_pk_mul_f32 v[18:19], v[18:19], v[2:3] op_sel_hi:[1,0]
	v_pk_mul_f32 v[16:17], v[16:17], v[2:3] op_sel_hi:[1,0]
